# prep phase gate-LoRA weight fragments loaded together into dead registers instead of one load-wait-MFMA at a time
# baseline (speedup 1.0000x reference)
; #define LAS __attribute__((address_space(3)))
; __device__ __forceinline__ void prep_phase(const Ctx& F, const float* mu, const float* w0, const float* a0, const float* k_k, const float* k_a, const float* r_k) {
;     ...
;         { const f32x4 m0 = *(const f32x4*)(mu + 1536 + j0), m1 = *(const f32x4*)(mu + 1540 + j0); muj[0] = m0.x; muj[1] = m0.y; muj[2] = m0.z; muj[3] = m0.w; muj[4] = m1.x; muj[5] = m1.y; muj[6] = m1.z; muj[7] = m1.w; }
; #pragma unroll
;         for (int i = 0; i < 2; ++i) { const int tt = (F.tid >> 5) + 16 * i; const int tok = t0 + tt;
;             const u32x4 pc = *(const u32x4*)(PRW + (size_t)tok * PRWW + 1536 + j0);
;             u32x4 pp = {0u, 0u, 0u, 0u}; if ((tok & (SEQ - 1)) != 0) pp = *(const u32x4*)(PRW + (size_t)(tok - 1) * PRWW + 1536 + j0);
;             float x[8] = {bflo(pc.x), bfhi(pc.x), bflo(pc.y), bfhi(pc.y), bflo(pc.z), bfhi(pc.z), bflo(pc.w), bfhi(pc.w)};
;             const float xp[8] = {bflo(pp.x), bfhi(pp.x), bflo(pp.y), bfhi(pp.y), bflo(pp.z), bfhi(pp.z), bflo(pp.w), bfhi(pp.w)};
; #pragma unroll
;             for (int e = 0; e < 8; ++e) { const float xs = x[e] + (xp[e] - x[e]) * muj[e]; const float y = typ == 0 ? 2.f * xs : xs; const float sg = __builtin_amdgcn_rcpf(1.f + __expf(-y));
;                 x[e] = typ == 0 ? 2.f * sg - 1.f : (typ == 1 ? xs : sg); }
;             u32x4 o; o.x = pk2(x[0], x[1]); o.y = pk2(x[2], x[3]); o.z = pk2(x[4], x[5]); o.w = pk2(x[6], x[7]);
;             *(LAS u32x4*)(act + tt * AP + j0) = o; }
;         __syncthreads();
; #pragma unroll
;         for (int nt = 0; nt < 2; ++nt) {
;             f32x16 aD, aA, aG;
; #pragma unroll
;             for (int r = 0; r < 16; ++r) { aD[r] = 0.f; aA[r] = 0.f; aG[r] = 0.f; }
;             const unsigned n = head * 64 + nt * 32 + j; const unsigned wo = n * 64 + 8 * hi, wg = n * 128 + 8 * hi; const unsigned ao = j * AP + 8 * hi;
; #pragma unroll
;             for (int ks = 0; ks < 4; ++ks) {
;                 aD = MFMA32(*(const bf16x8*)(LWD + wo + ks * 16), *(const LAS bf16x8*)(act + ao + ks * 16), aD);
;                 aA = MFMA32(*(const bf16x8*)(LWA + wo + ks * 16), *(const LAS bf16x8*)(act + ao + (64 + ks * 16)), aA); }
; #pragma unroll
;             for (int ks = 0; ks < 8; ++ks)
;                 aG = MFMA32(*(const bf16x8*)(LWG + wg + ks * 16), *(const LAS bf16x8*)(act + ao + (128 + ks * 16)), aG);
.LBB0_528:
	s_or_b64 exec, exec, s[26:27]
	s_waitcnt vmcnt(0)
	v_cvt_f32_f16_e32 v18, v14
	v_cvt_f32_f16_e32 v20, v6
	v_cvt_f32_f16_sdwa v19, v14 dst_sel:DWORD dst_unused:UNUSED_PAD src0_sel:WORD_1
	v_cvt_f32_f16_sdwa v6, v6 dst_sel:DWORD dst_unused:UNUSED_PAD src0_sel:WORD_1
	v_add_u32_e32 v251, 0x4000, v165
	v_sub_f32_e32 v18, v20, v18
	v_fma_mix_f32 v10, v10, v18, v14 op_sel_hi:[0,0,1]
	v_add_f32_e32 v18, v10, v10
	v_cndmask_b32_e64 v18, v18, v10, s[10:11]
	v_mul_f32_e32 v18, 0xbfb8aa3b, v18
	v_exp_f32_e32 v18, v18
	v_sub_f32_e32 v6, v6, v19
	v_fma_mix_f32 v6, v11, v6, v14 op_sel:[0,0,1] op_sel_hi:[0,0,1]
	v_cvt_f32_f16_e32 v14, v7
	v_add_f32_e32 v18, 1.0, v18
	v_rcp_f32_e32 v18, v18
	v_add_u32_e32 v252, 0xc000, v165
	s_ashr_i32 s26, s33, 31
	s_lshr_b32 s26, s26, 25
	v_fma_f32 v20, v18, 2.0, -1.0
	v_cndmask_b32_e64 v10, v18, v10, s[4:5]
	v_cndmask_b32_e64 v18, v20, v10, s[10:11]
	v_add_f32_e32 v10, v6, v6
	v_cndmask_b32_e64 v10, v10, v6, s[10:11]
	v_mul_f32_e32 v10, 0xbfb8aa3b, v10
	v_exp_f32_e32 v10, v10
	s_add_i32 s26, s33, s26
	s_ashr_i32 s26, s26, 7
	s_lshl_b32 s26, s26, 3
	v_add_f32_e32 v10, 1.0, v10
	v_rcp_f32_e32 v10, v10
	s_add_i32 s26, s26, s86
	s_ashr_i32 s27, s26, 31
	v_fma_f32 v11, v10, 2.0, -1.0
	v_cndmask_b32_e64 v6, v10, v6, s[4:5]
	v_cndmask_b32_e64 v19, v11, v6, s[10:11]
	v_cvt_f32_f16_sdwa v11, v15 dst_sel:DWORD dst_unused:UNUSED_PAD src0_sel:WORD_1
	v_cvt_f32_f16_e32 v10, v15
	v_cvt_f32_f16_sdwa v15, v7 dst_sel:DWORD dst_unused:UNUSED_PAD src0_sel:WORD_1
	v_pk_add_f32 v[6:7], v[14:15], v[10:11] neg_lo:[0,1] neg_hi:[0,1]
	s_nop 0
	v_pk_fma_f32 v[6:7], v[12:13], v[6:7], v[10:11]
	s_nop 0
	v_add_f32_e32 v10, v6, v6
	v_add_f32_e32 v11, v7, v7
	v_cndmask_b32_e64 v10, v10, v6, s[10:11]
	v_cndmask_b32_e64 v11, v11, v7, s[10:11]
	v_mul_f32_e32 v10, 0xbfb8aa3b, v10
	v_mul_f32_e32 v11, 0xbfb8aa3b, v11
	v_exp_f32_e32 v10, v10
	v_exp_f32_e32 v11, v11
	v_add_f32_e32 v10, 1.0, v10
	v_add_f32_e32 v11, 1.0, v11
	v_rcp_f32_e32 v10, v10
	v_rcp_f32_e32 v11, v11
	v_cndmask_b32_e64 v6, v10, v6, s[4:5]
	v_pk_fma_f32 v[12:13], v[10:11], 2.0, -1.0 op_sel_hi:[1,0,0]
	v_cndmask_b32_e64 v7, v11, v7, s[4:5]
	v_cndmask_b32_e64 v13, v13, v7, s[10:11]
	v_cndmask_b32_e64 v12, v12, v6, s[10:11]
	v_cvt_f32_f16_sdwa v7, v16 dst_sel:DWORD dst_unused:UNUSED_PAD src0_sel:WORD_1
	v_cvt_f32_f16_e32 v6, v16
	v_cvt_f32_f16_sdwa v11, v8 dst_sel:DWORD dst_unused:UNUSED_PAD src0_sel:WORD_1
	v_cvt_f32_f16_e32 v10, v8
	v_pk_add_f32 v[10:11], v[10:11], v[6:7] neg_lo:[0,1] neg_hi:[0,1]
	s_nop 0
	v_pk_fma_f32 v[2:3], v[2:3], v[10:11], v[6:7]
	s_nop 0
	v_add_f32_e32 v6, v2, v2
	v_add_f32_e32 v7, v3, v3
	v_cndmask_b32_e64 v6, v6, v2, s[10:11]
	v_cndmask_b32_e64 v7, v7, v3, s[10:11]
	v_mul_f32_e32 v6, 0xbfb8aa3b, v6
	v_mul_f32_e32 v7, 0xbfb8aa3b, v7
	v_exp_f32_e32 v6, v6
	v_exp_f32_e32 v7, v7
	v_add_f32_e32 v6, 1.0, v6
	v_add_f32_e32 v7, 1.0, v7
	v_rcp_f32_e32 v6, v6
	v_rcp_f32_e32 v7, v7
	v_cndmask_b32_e64 v2, v6, v2, s[4:5]
	v_pk_fma_f32 v[10:11], v[6:7], 2.0, -1.0 op_sel_hi:[1,0,0]
	v_cndmask_b32_e64 v3, v7, v3, s[4:5]
	v_cndmask_b32_e64 v8, v11, v3, s[10:11]
	v_cndmask_b32_e64 v10, v10, v2, s[10:11]
	v_cvt_f32_f16_sdwa v3, v17 dst_sel:DWORD dst_unused:UNUSED_PAD src0_sel:WORD_1
	v_cvt_f32_f16_e32 v2, v17
	v_cvt_f32_f16_sdwa v7, v9 dst_sel:DWORD dst_unused:UNUSED_PAD src0_sel:WORD_1
	v_cvt_f32_f16_e32 v6, v9
	v_pk_add_f32 v[6:7], v[6:7], v[2:3] neg_lo:[0,1] neg_hi:[0,1]
	s_nop 0
	v_pk_fma_f32 v[2:3], v[4:5], v[6:7], v[2:3]
	s_nop 0
	v_add_f32_e32 v4, v2, v2
	v_add_f32_e32 v5, v3, v3
	v_cndmask_b32_e64 v4, v4, v2, s[10:11]
	v_cndmask_b32_e64 v5, v5, v3, s[10:11]
	v_mul_f32_e32 v4, 0xbfb8aa3b, v4
	v_mul_f32_e32 v5, 0xbfb8aa3b, v5
	v_exp_f32_e32 v4, v4
	v_exp_f32_e32 v5, v5
	v_add_f32_e32 v4, 1.0, v4
	v_add_f32_e32 v5, 1.0, v5
	v_rcp_f32_e32 v4, v4
	v_rcp_f32_e32 v5, v5
	v_cndmask_b32_e64 v2, v4, v2, s[4:5]
	v_pk_fma_f32 v[6:7], v[4:5], 2.0, -1.0 op_sel_hi:[1,0,0]
	v_cndmask_b32_e64 v3, v5, v3, s[4:5]
	v_cndmask_b32_e64 v5, v7, v3, s[10:11]
	v_cndmask_b32_e64 v6, v6, v2, s[10:11]
	v_cvt_pk_f16_f32 v2, v18, v19
	v_cvt_pk_f16_f32 v3, v12, v13
	v_cvt_pk_f16_f32 v4, v10, v8
	v_cvt_pk_f16_f32 v5, v6, v5
	ds_write_b128 v227, v[2:5] offset:8448
	s_waitcnt lgkmcnt(0)
	s_barrier
	global_load_dwordx4 v[18:21], v[142:143], off
	global_load_dwordx4 v[34:37], v[144:145], off
	ds_read_b128 v[74:77], v159 offset:128
	global_load_dwordx4 v[94:97], v[142:143], off offset:32
	ds_read_b128 v[78:81], v159
	ds_read_b128 v[70:73], v159 offset:32
	global_load_dwordx4 v[134:137], v[144:145], off offset:96
	global_load_dwordx4 v[2:5], v[146:147], off
	global_load_dwordx4 v[22:25], v[146:147], off offset:32
	ds_read_b128 v[50:53], v159 offset:224
	ds_read_b128 v[98:101], v159 offset:256
	ds_read_b128 v[102:105], v159 offset:288
	ds_read_b128 v[110:113], v159 offset:320
	ds_read_b128 v[114:117], v159 offset:352
	ds_read_b128 v[106:109], v159 offset:384
	ds_read_b128 v[90:93], v159 offset:416
	ds_read_b128 v[86:89], v159 offset:448
	global_load_dwordx4 v[118:121], v[144:145], off offset:32
	global_load_dwordx4 v[126:129], v[144:145], off offset:64
	global_load_dwordx4 v[122:125], v[142:143], off offset:64
	global_load_dwordx4 v[130:133], v[142:143], off offset:96
	ds_read_b128 v[82:85], v159 offset:480
	ds_read_b128 v[66:69], v159 offset:160
	ds_read_b128 v[58:61], v159 offset:192
	ds_read_b128 v[62:65], v159 offset:64
	ds_read_b128 v[54:57], v159 offset:96
	s_waitcnt vmcnt(8) lgkmcnt(14)
	v_mfma_f32_32x32x16_f16 v[34:49], v[34:37], v[74:77], 0
	s_waitcnt vmcnt(5) lgkmcnt(11)
	v_mfma_f32_32x32x16_f16 v[2:17], v[2:5], v[98:101], 0
	s_waitcnt vmcnt(4) lgkmcnt(10)
; #define LAS __attribute__((address_space(3)))
; #define MFMA32(a, b, c) __builtin_amdgcn_mfma_f32_32x32x16_f16(H8(a), H8(b), (c), 0, 0, 0)
; __device__ __forceinline__ u32x2 pack4(f32x4 v) { u32x2 o; o.x = pk2(v.x, v.y); o.y = pk2(v.z, v.w); return o; }
; __device__ __forceinline__ void prep_phase(const Ctx& F, const float* mu, const float* w0, const float* a0, const float* k_k, const float* k_a, const float* r_k) {
;     ...
;         for (int nt = 0; nt < 2; ++nt) {
;             f32x16 aD, aA, aG;
; #pragma unroll
;             for (int r = 0; r < 16; ++r) { aD[r] = 0.f; aA[r] = 0.f; aG[r] = 0.f; }
;             const unsigned n = head * 64 + nt * 32 + j; const unsigned wo = n * 64 + 8 * hi, wg = n * 128 + 8 * hi; const unsigned ao = j * AP + 8 * hi;
; #pragma unroll
;             for (int ks = 0; ks < 4; ++ks) {
;                 aD = MFMA32(*(const bf16x8*)(LWD + wo + ks * 16), *(const LAS bf16x8*)(act + ao + ks * 16), aD);
;                 aA = MFMA32(*(const bf16x8*)(LWA + wo + ks * 16), *(const LAS bf16x8*)(act + ao + (64 + ks * 16)), aA); }
; #pragma unroll
;             for (int ks = 0; ks < 8; ++ks)
;                 aG = MFMA32(*(const bf16x8*)(LWG + wg + ks * 16), *(const LAS bf16x8*)(act + ao + (128 + ks * 16)), aG);
;             LAS bf16* ob = outs + j * OP + head * 64 + nt * 32 + 4 * hi;
; #pragma unroll
;             for (int q = 0; q < 4; ++q) {
;                 *(LAS u32x2*)(ob + 8 * q) = pack4((f32x4){aD[4 * q], aD[4 * q + 1], aD[4 * q + 2], aD[4 * q + 3]});
;                 *(LAS u32x2*)(ob + 32 * OP + 8 * q) = pack4((f32x4){aA[4 * q], aA[4 * q + 1], aA[4 * q + 2], aA[4 * q + 3]});
;                 *(LAS u32x2*)(ob + 64 * OP + 8 * q) = pack4((f32x4){aG[4 * q], aG[4 * q + 1], aG[4 * q + 2], aG[4 * q + 3]}); }
	v_mfma_f32_32x32x16_f16 v[2:17], v[22:25], v[102:105], v[2:17]
	global_load_dwordx4 v[22:25], v[146:147], off offset:64
	s_waitcnt vmcnt(4) lgkmcnt(3)
	v_mfma_f32_32x32x16_f16 v[34:49], v[118:121], v[66:69], v[34:49]
	s_waitcnt vmcnt(3) lgkmcnt(2)
	v_mfma_f32_32x32x16_f16 v[34:49], v[126:129], v[58:61], v[34:49]
	v_mfma_f32_32x32x16_f16 v[34:49], v[134:137], v[50:53], v[34:49]
	global_load_dwordx4 v[118:121], v[146:147], off offset:96
	global_load_dwordx4 v[126:129], v[146:147], off offset:128
	global_load_dwordx4 v[134:137], v[146:147], off offset:160
	s_waitcnt vmcnt(3)
	v_mfma_f32_32x32x16_f16 v[2:17], v[22:25], v[110:113], v[2:17]
	global_load_dwordx4 v[22:25], v[146:147], off offset:192
	s_waitcnt vmcnt(3)
	v_mfma_f32_32x32x16_f16 v[2:17], v[118:121], v[114:117], v[2:17]
	global_load_dwordx4 v[118:121], v[146:147], off offset:224
	s_waitcnt vmcnt(3)
	v_mfma_f32_32x32x16_f16 v[2:17], v[126:129], v[106:109], v[2:17]
	s_waitcnt vmcnt(2)
	v_mfma_f32_32x32x16_f16 v[2:17], v[134:137], v[90:93], v[2:17]
	s_waitcnt vmcnt(1)
	v_mfma_f32_32x32x16_f16 v[2:17], v[22:25], v[86:89], v[2:17]
	s_waitcnt vmcnt(0)
	v_mfma_f32_32x32x16_f16 v[2:17], v[118:121], v[82:85], v[2:17]
	s_nop 11
	v_cvt_pk_f16_f32 v2, v2, v3
	v_mfma_f32_32x32x16_f16 v[18:33], v[18:21], v[78:81], 0
	v_cvt_pk_f16_f32 v3, v4, v5
	ds_write_b64 v166, v[2:3]
	v_cvt_pk_f16_f32 v4, v42, v43
	v_cvt_pk_f16_f32 v5, v44, v45
	v_mfma_f32_32x32x16_f16 v[18:33], v[94:97], v[70:73], v[18:33]
	s_waitcnt lgkmcnt(2)
	v_mfma_f32_32x32x16_f16 v[18:33], v[122:125], v[62:65], v[18:33]
	s_waitcnt lgkmcnt(1)
	v_mfma_f32_32x32x16_f16 v[18:33], v[130:133], v[54:57], v[18:33]
	s_nop 11
	v_cvt_pk_f16_f32 v18, v18, v19
	v_cvt_pk_f16_f32 v19, v20, v21
	v_cvt_pk_f16_f32 v2, v22, v23
	v_cvt_pk_f16_f32 v3, v24, v25
	v_cvt_pk_f16_f32 v20, v34, v35
	v_cvt_pk_f16_f32 v21, v36, v37
	ds_write2_b64 v251, v[18:19], v[2:3] offset0:64 offset1:66
	v_cvt_pk_f16_f32 v2, v38, v39
	v_cvt_pk_f16_f32 v3, v40, v41
	ds_write2_b64 v252, v[20:21], v[2:3] offset0:128 offset1:130
	v_cvt_pk_f16_f32 v2, v6, v7
	v_cvt_pk_f16_f32 v3, v8, v9
	v_cvt_pk_f16_f32 v6, v10, v11
	v_cvt_pk_f16_f32 v7, v12, v13
	ds_write_b64 v167, v[2:3]
	v_cvt_pk_f16_f32 v2, v26, v27
	v_cvt_pk_f16_f32 v3, v28, v29
	ds_write_b64 v168, v[6:7]
	v_cvt_pk_f16_f32 v6, v30, v31
	v_cvt_pk_f16_f32 v7, v32, v33
	ds_write2_b64 v251, v[2:3], v[6:7] offset0:68 offset1:70
	v_cvt_pk_f16_f32 v2, v46, v47
	v_cvt_pk_f16_f32 v3, v48, v49
	ds_write2_b64 v252, v[4:5], v[2:3] offset0:132 offset1:134
	v_cvt_pk_f16_f32 v2, v14, v15
	v_cvt_pk_f16_f32 v3, v16, v17
	ds_write_b64 v169, v[2:3]
	global_load_dwordx4 v[22:25], v[148:149], off
	global_load_dwordx4 v[18:21], v[150:151], off
	global_load_dwordx4 v[134:137], v[148:149], off offset:32
	global_load_dwordx4 v[130:133], v[150:151], off offset:32
	global_load_dwordx4 v[126:129], v[148:149], off offset:64
	global_load_dwordx4 v[122:125], v[150:151], off offset:64
	global_load_dwordx4 v[118:121], v[148:149], off offset:96
	global_load_dwordx4 v[94:97], v[150:151], off offset:96
	global_load_dwordx4 v[2:5], v[152:153], off
	global_load_dwordx4 v[26:29], v[152:153], off offset:32
	global_load_dwordx4 v[30:33], v[152:153], off offset:64
	global_load_dwordx4 v[34:37], v[152:153], off offset:96
	global_load_dwordx4 v[38:41], v[152:153], off offset:128
	global_load_dwordx4 v[42:45], v[152:153], off offset:160
	global_load_dwordx4 v[46:49], v[152:153], off offset:192
	s_waitcnt vmcnt(6)
	v_mfma_f32_32x32x16_f16 v[2:17], v[2:5], v[98:101], 0
	s_waitcnt vmcnt(5)
	v_mfma_f32_32x32x16_f16 v[2:17], v[26:29], v[102:105], v[2:17]
	global_load_dwordx4 v[26:29], v[152:153], off offset:224
	s_waitcnt vmcnt(5)
	v_mfma_f32_32x32x16_f16 v[2:17], v[30:33], v[110:113], v[2:17]
	s_waitcnt vmcnt(4)
	v_mfma_f32_32x32x16_f16 v[2:17], v[34:37], v[114:117], v[2:17]
	s_waitcnt vmcnt(3)
	v_mfma_f32_32x32x16_f16 v[2:17], v[38:41], v[106:109], v[2:17]
	s_waitcnt vmcnt(2)
	v_mfma_f32_32x32x16_f16 v[2:17], v[42:45], v[90:93], v[2:17]
	s_waitcnt vmcnt(1)
	v_mfma_f32_32x32x16_f16 v[2:17], v[46:49], v[86:89], v[2:17]
	s_waitcnt vmcnt(0)
	v_mfma_f32_32x32x16_f16 v[2:17], v[26:29], v[82:85], v[2:17]
	v_mfma_f32_32x32x16_f16 v[34:49], v[22:25], v[78:81], 0
	s_nop 11
	v_cvt_pk_f16_f32 v2, v2, v3
	v_mfma_f32_32x32x16_f16 v[18:33], v[18:21], v[74:77], 0
	v_cvt_pk_f16_f32 v3, v4, v5
	ds_write_b64 v138, v[2:3]
	v_mfma_f32_32x32x16_f16 v[34:49], v[134:137], v[70:73], v[34:49]
	v_mfma_f32_32x32x16_f16 v[18:33], v[130:133], v[66:69], v[18:33]
	v_mfma_f32_32x32x16_f16 v[34:49], v[126:129], v[62:65], v[34:49]
	v_mfma_f32_32x32x16_f16 v[18:33], v[122:125], v[58:61], v[18:33]
	v_mfma_f32_32x32x16_f16 v[34:49], v[118:121], v[54:57], v[34:49]
	v_mfma_f32_32x32x16_f16 v[18:33], v[94:97], v[50:53], v[18:33]
	s_nop 10
	v_cvt_pk_f16_f32 v34, v34, v35
	v_cvt_pk_f16_f32 v35, v36, v37
	v_cvt_pk_f16_f32 v2, v38, v39
	v_cvt_pk_f16_f32 v3, v40, v41
	ds_write2_b64 v251, v[34:35], v[2:3] offset0:72 offset1:74
	v_cvt_pk_f16_f32 v18, v18, v19
	v_cvt_pk_f16_f32 v19, v20, v21
	v_cvt_pk_f16_f32 v2, v22, v23
	v_cvt_pk_f16_f32 v3, v24, v25
	ds_write2_b64 v252, v[18:19], v[2:3] offset0:136 offset1:138
	v_cvt_pk_f16_f32 v2, v6, v7
	v_cvt_pk_f16_f32 v3, v8, v9
	v_cvt_pk_f16_f32 v6, v10, v11
	v_cvt_pk_f16_f32 v7, v12, v13
	v_cvt_f32_f16_e32 v11, v250
	ds_write_b64 v172, v[2:3]
	v_cvt_pk_f16_f32 v2, v42, v43
	v_cvt_pk_f16_f32 v3, v44, v45
	ds_write_b64 v173, v[6:7]
	v_cvt_pk_f16_f32 v6, v46, v47
	v_cvt_pk_f16_f32 v7, v48, v49
	v_cvt_f32_f16_e32 v12, v249
	v_cvt_pk_f16_f32 v4, v26, v27
	v_cvt_pk_f16_f32 v5, v28, v29
	ds_write2_b64 v251, v[2:3], v[6:7] offset0:76 offset1:78
	v_cvt_pk_f16_f32 v2, v30, v31
	v_cvt_pk_f16_f32 v3, v32, v33
	ds_write2_b64 v252, v[4:5], v[2:3] offset0:140 offset1:142
	v_cvt_pk_f16_f32 v2, v14, v15
	v_cvt_pk_f16_f32 v3, v16, v17
	v_add_u32_e32 v4, 0x5c00, v229
	v_add_u32_e32 v6, 0x5400, v229
	ds_write_b64 v174, v[2:3]
	s_waitcnt lgkmcnt(0)
	s_barrier
; __device__ __forceinline__ bf16 f2bf(float f) { return (bf16)(pk2(f, 0.f) & 0xffffu); }
; __device__ __forceinline__ float bf2f(bf16 b) { return (float)__builtin_bit_cast(_Float16, b); }
; __device__ __forceinline__ void prep_phase(const Ctx& F, const float* mu, const float* w0, const float* a0, const float* k_k, const float* k_a, const float* r_k) {
;     ...
;         for (int t = 0; t < 32; ++t) {
;             if (t + 6 < 32) { rin[t + 7] = PRL((t + 6) * PRWW); kin[t + 7] = PRL((t + 6) * PRWW + 512); vin[t + 7] = PRL((t + 6) * PRWW + 1024); }
;             asm volatile("" ::: "memory");
;             const float rc = bf2f(rin[t + 1]), kc = bf2f(kin[t + 1]), vc = bf2f(vin[t + 1]), rp = bf2f(rin[t]), kp = bf2f(kin[t]), vp = bf2f(vin[t]);
;             const float r = rc + (rp - rc) * mur, kx = kc + (kp - kc) * muk, vx = vc + (vp - vc) * muv;
;             const float ld = bf2f(outs[t * OP + c]), la = bf2f(outs[32 * OP + t * OP + c]), g = bf2f(outs[64 * OP + t * OP + c]);
;             const float een = -0.87504979f * __builtin_amdgcn_rcpf(1.f + __builtin_amdgcn_exp2f(w0n - 1.44269504f * ld));
;             const float omw = 1.f - __builtin_amdgcn_exp2f(een);
;             const float a = __builtin_amdgcn_rcpf(1.f + __builtin_amdgcn_exp2f(a0n - 1.44269504f * la));
;             const float kkv = kx * kkc; const float n2 = wave_sum_d(kkv * kkv); const float kk = kkv * __builtin_amdgcn_rsqf(fmaxf(n2, 1e-24f));
;             const float kmod = kx * (1.f + (a - 1.f) * kac); const float bb = kk * a;
;             float s_kr = kmod * r, s_bs = s_kr * rkc, s_br = bb * r;
;             wave_sum3(s_kr, s_bs, s_br, lane);
;             const float wr = (1.f - omw) * r - s_br * kk;
;             const unsigned o = ob0 + t * 128u;
;             ST16(SWR, o, f2bf(wr)); ST16(SC, o, f2bf(omw)); ST16(SK, o, f2bf(kmod)); ST16(SV, o, f2bf(vx)); ST16(SKK, o, f2bf(kk)); ST16(SB, o, f2bf(bb));
;             ST16(GG, gb0 + t * 1024u, f2bf(g));
;             if (lane == 0) *(f32x2*)(SCAL + ((size_t)bh * SEQ + pos0 + t) * 2) = (f32x2){s_kr, s_bs};
	v_add_u32_e32 v5, 0x5800, v229
	global_load_ushort v8, v6, s[12:13]
	global_load_ushort v7, v5, s[12:13]
	s_nop 0
	global_load_ushort v6, v4, s[12:13]
	v_sub_f32_e32 v4, v246, v11
	v_fma_mix_f32 v9, v161, v4, v250 op_sel_hi:[0,0,1]
	v_sub_f32_e32 v4, v247, v12
	v_fma_mix_f32 v13, v160, v4, v249 op_sel_hi:[0,0,1]
	ds_read_u16 v4, v176 offset:16896
	ds_read_u16 v5, v176 offset:50176
	ds_read_u16 v15, v177
	v_mul_f32_e32 v18, v1, v13
	v_lshl_or_b32 v2, s28, 7, v175
	s_waitcnt lgkmcnt(2)
	v_fma_mix_f32 v4, v4, s31, v170 op_sel_hi:[1,0,0]
	v_lshl_or_b32 v3, s26, 19, v2
	v_exp_f32_e32 v4, v4
	s_lshl_b64 s[26:27], s[26:27], 12
	s_or_b32 s26, s26, s28
	v_cvt_f32_f16_e32 v10, v245
	v_add_f32_e32 v4, 1.0, v4
	v_rcp_f32_e32 v4, v4
	v_add_u32_e32 v2, s38, v158
	v_sub_f32_e32 v14, v248, v10
	v_mul_f32_e32 v4, 0xbf600343, v4
	v_exp_f32_e32 v4, v4
	s_nop 0
	v_sub_f32_e32 v16, 1.0, v4
	s_waitcnt lgkmcnt(1)
	v_fma_mix_f32 v4, v5, s31, v171 op_sel_hi:[1,0,0]
	v_mov_b32_e32 v5, 0
	v_exp_f32_e32 v4, v4
	s_nop 0
	v_add_f32_e32 v4, 1.0, v4
	v_rcp_f32_e32 v17, v4
	v_mul_f32_e32 v4, v18, v18
	s_nop 1
	v_mov_b32_dpp v5, v4 quad_perm:[1,0,3,2] row_mask:0xf bank_mask:0xf
	v_fmac_f32_e32 v5, v18, v18
	s_nop 1
	v_add_f32_dpp v4, v5, v5 quad_perm:[2,3,0,1] row_mask:0xf bank_mask:0xf bound_ctrl:1
	v_mov_b32_e32 v5, 0
	s_nop 0
	v_add_f32_dpp v4, v4, v4 row_half_mirror row_mask:0xf bank_mask:0xf bound_ctrl:1
	s_nop 1
	v_add_f32_dpp v4, v4, v4 row_mirror row_mask:0xf bank_mask:0xf bound_ctrl:1
	s_nop 1
	v_mov_b32_dpp v5, v4 row_bcast:15 row_mask:0xa bank_mask:0xf
	v_add_f32_e32 v4, v4, v5
	v_mov_b32_e32 v5, 0
	s_nop 1
	v_mov_b32_dpp v5, v4 row_bcast:31 row_mask:0xc bank_mask:0xf
	v_add_f32_e32 v4, v4, v5
	s_nop 0
	v_readlane_b32 s28, v4, 63
	s_nop 1
	v_max_f32_e64 v4, s28, s28
	v_max_f32_e32 v4, 0x179abe15, v4
	v_rsq_f32_e32 v19, v4
	v_add_f32_e32 v4, -1.0, v17
	v_fma_f32 v21, v156, v4, 1.0
	v_mul_f32_e32 v4, v13, v21
	v_mul_f32_e32 v20, v18, v19
	v_mul_f32_e32 v5, v17, v20
	v_mul_f32_e32 v4, v9, v4
	v_mul_f32_e32 v22, v157, v4
	v_mul_f32_e32 v5, v9, v5
	v_cndmask_b32_e64 v23, v5, v4, s[6:7]
	v_cndmask_b32_e64 v4, v4, v5, s[6:7]
	v_cndmask_b32_e64 v5, 0, v22, s[6:7]
	v_cndmask_b32_e64 v22, v22, 0, s[6:7]
	v_add_f32_dpp v4, v4, v23 quad_perm:[1,0,3,2] row_mask:0xf bank_mask:0xf bound_ctrl:1
	s_nop 0
	v_add_f32_dpp v5, v22, v5 quad_perm:[1,0,3,2] row_mask:0xf bank_mask:0xf bound_ctrl:1
	v_cndmask_b32_e64 v22, v5, v4, s[8:9]
	v_cndmask_b32_e64 v4, v4, v5, s[8:9]
	s_nop 1
	v_add_f32_dpp v4, v4, v22 quad_perm:[2,3,0,1] row_mask:0xf bank_mask:0xf bound_ctrl:1
	v_and_b32_e32 v22, 64, v228
	v_add_u32_e32 v22, 64, v22
	v_add_f32_dpp v4, v4, v4 row_ror:4 row_mask:0xf bank_mask:0xf bound_ctrl:1
	s_nop 1
	v_add_f32_dpp v5, v4, v4 row_ror:8 row_mask:0xf bank_mask:0xf bound_ctrl:1
	v_xor_b32_e32 v4, 16, v228
	v_cmp_lt_i32_e32 vcc, v4, v22
	s_nop 1
	v_cndmask_b32_e32 v4, v228, v4, vcc
	v_lshlrev_b32_e32 v4, 2, v4
	ds_bpermute_b32 v23, v4, v5
	s_waitcnt lgkmcnt(0)
	v_add_f32_e32 v23, v5, v23
	v_xor_b32_e32 v5, 32, v228
	v_cmp_lt_i32_e32 vcc, v5, v22
	s_nop 1
	v_cndmask_b32_e32 v5, v228, v5, vcc
	v_lshlrev_b32_e32 v5, 2, v5
	ds_bpermute_b32 v22, v5, v23
	s_waitcnt lgkmcnt(0)
	v_add_f32_e32 v22, v23, v22
	s_nop 0
	v_readlane_b32 s28, v22, 1
	v_readlane_b32 s42, v22, 0
	v_readlane_b32 s43, v22, 2
	v_sub_f32_e32 v22, 1.0, v16
	v_mul_f32_e32 v23, s28, v20
	v_fma_mixlo_f16 v9, v9, v22, -v23
	global_store_short v3, v9, s[66:67]
	v_cvt_f16_f32_e32 v9, v16
	global_store_short v3, v9, s[14:15]
	v_fma_mixlo_f16 v9, v13, v21, 0
	global_store_short v3, v9, s[16:17]
	v_fma_mixlo_f16 v9, v164, v14, v245 op_sel_hi:[0,0,1]
	global_store_short v3, v9, s[18:19]
	v_fma_mixlo_f16 v9, v18, v19, 0
	global_store_short v3, v9, s[20:21]
	v_fma_mixlo_f16 v9, v17, v20, 0
	global_store_short v3, v9, s[22:23]
	global_store_short v2, v15, s[24:25]
	s_and_saveexec_b64 s[28:29], s[2:3]
	s_cbranch_execz .LBB0_530
	s_lshl_b64 s[44:45], s[26:27], 3
	s_add_u32 s44, s34, s44
	s_addc_u32 s45, s35, s45
	v_mov_b32_e32 v14, s42
	v_mov_b32_e32 v15, s43
	global_store_dwordx2 v139, v[14:15], s[44:45]
